# GEMM1 tile order: affine permutation (35p+15 mod 52) of the column-tile index so no workgroup gets 3 transposed tiles plus a new_v tile
# speedup vs baseline: 1.0014x; 1.0014x over previous
.LBB0_196:
	s_or_b64 exec, exec, s[2:3]
	s_add_u32 s8, s14, 0x13200000
	s_addc_u32 s9, s15, 0
	s_cmpk_lt_i32 s62, 0x180
	s_cselect_b64 s[0:1], -1, 0
	v_writelane_b32 v253, s0, 33
	v_mbcnt_hi_u32_b32 v228, -1, v10
	v_and_b32_e32 v2, 64, v228
	v_writelane_b32 v253, s1, 34
	s_add_u32 s0, s14, 0xa000000
	v_writelane_b32 v253, s0, 35
	s_addc_u32 s0, s15, 0
	s_cmp_eq_u32 s42, 15
	v_writelane_b32 v253, s0, 36
	s_cselect_b64 s[0:1], -1, 0
	v_writelane_b32 v253, s0, 37
	s_cmp_eq_u32 s42, 14
	s_waitcnt lgkmcnt(0)
	v_writelane_b32 v253, s1, 38
	s_cselect_b64 s[0:1], -1, 0
	v_writelane_b32 v253, s0, 39
	s_cmp_eq_u32 s42, 13
	s_barrier
	v_writelane_b32 v253, s1, 40
	s_cselect_b64 s[0:1], -1, 0
	v_writelane_b32 v253, s0, 41
	s_cmp_eq_u32 s42, 12
	s_nop 0
	v_writelane_b32 v253, s1, 42
	s_cselect_b64 s[0:1], -1, 0
	v_writelane_b32 v253, s0, 43
	s_cmp_eq_u32 s42, 11
	s_mov_b32 s83, 0x20000
	v_writelane_b32 v253, s1, 44
	s_cselect_b64 s[0:1], -1, 0
	v_writelane_b32 v253, s0, 45
	s_cmp_eq_u32 s42, 10
	s_mov_b32 s82, 0x3000000
	v_writelane_b32 v253, s1, 46
	s_cselect_b64 s[0:1], -1, 0
	v_writelane_b32 v253, s0, 47
	s_cmp_eq_u32 s42, 9
	v_mov_b32_e32 v0, 0
	v_writelane_b32 v253, s1, 48
	s_cselect_b64 s[0:1], -1, 0
	v_writelane_b32 v253, s0, 49
	s_cmp_eq_u32 s42, 8
	v_mov_b32_e32 v221, 0x358637bd
	v_writelane_b32 v253, s1, 50
	s_cselect_b64 s[0:1], -1, 0
	v_writelane_b32 v253, s0, 51
	s_cmp_eq_u32 s42, 7
	v_mov_b32_e32 v222, 0xc0447cbd
	v_writelane_b32 v253, s1, 52
	s_cselect_b64 s[0:1], -1, 0
	v_writelane_b32 v253, s0, 53
	s_cmp_eq_u32 s42, 6
	v_mov_b32_e32 v223, 1
	v_writelane_b32 v253, s1, 54
	s_cselect_b64 s[0:1], -1, 0
	v_writelane_b32 v253, s0, 55
	s_cmp_eq_u32 s42, 5
	v_mov_b32_e32 v198, 1.0
	v_writelane_b32 v253, s1, 56
	s_cselect_b64 s[0:1], -1, 0
	v_writelane_b32 v253, s0, 57
	s_cmp_eq_u32 s42, 4
	v_mov_b32_e32 v224, 0x3000
	v_writelane_b32 v253, s1, 58
	s_cselect_b64 s[0:1], -1, 0
	v_writelane_b32 v253, s0, 59
	s_cmp_eq_u32 s42, 3
	v_mov_b32_e32 v225, 0x1000
	v_writelane_b32 v253, s1, 60
	s_cselect_b64 s[0:1], -1, 0
	v_writelane_b32 v253, s0, 61
	s_cmp_eq_u32 s42, 2
	v_mov_b32_e32 v226, 0x2000
	v_writelane_b32 v253, s1, 62
	s_cselect_b64 s[0:1], -1, 0
	v_writelane_b32 v253, s0, 63
	s_cmp_eq_u32 s42, 1
	v_mov_b32_e32 v227, 0x4000
	v_writelane_b32 v254, s1, 0
	s_cselect_b64 s[0:1], -1, 0
	v_writelane_b32 v254, s0, 1
	s_cmp_eq_u32 s42, 0
	v_add_u32_e32 v229, 64, v2
	v_writelane_b32 v254, s1, 2
	s_cselect_b64 s[0:1], -1, 0
	s_add_u32 s94, s14, 0x16200000
	s_addc_u32 s95, s15, 0
	s_add_u32 s84, s12, 0xa000000
	s_addc_u32 s85, s13, 0
	v_writelane_b32 v254, s0, 3
	s_cmpk_lt_i32 s62, 0x9c0
	v_xor_b32_e32 v230, 1, v228
	v_writelane_b32 v254, s1, 4
	s_cselect_b64 s[0:1], -1, 0
	v_writelane_b32 v254, s0, 5
	s_ashr_i32 s57, s62, 31
	v_xor_b32_e32 v231, 2, v228
	v_writelane_b32 v254, s1, 6
	s_lshr_b32 s0, s57, 29
	s_add_i32 s0, s62, s0
	s_ashr_i32 s2, s0, 3
	s_and_b32 s0, s0, -8
	s_sub_i32 s3, s62, s0
	s_ashr_i32 s0, s60, 31
	s_add_u32 s6, s14, 0x2d600000
	s_addc_u32 s7, s15, 0
	v_writelane_b32 v254, s0, 7
	s_add_u32 s0, s14, 0x8c00000
	v_writelane_b32 v254, s0, 8
	s_addc_u32 s0, s15, 0
	v_writelane_b32 v254, s0, 9
	s_add_u32 s0, s14, 0x29a00000
	v_writelane_b32 v254, s0, 10
	s_addc_u32 s0, s15, 0
	v_writelane_b32 v254, s0, 11
	s_add_u32 s0, s12, 0x6000000
	v_writelane_b32 v254, s0, 12
	s_addc_u32 s0, s13, 0
	v_writelane_b32 v254, s0, 13
	s_add_u32 s0, s14, 0x2a600000
	s_addc_u32 s1, s15, 0
	v_writelane_b32 v254, s0, 14
	v_xor_b32_e32 v232, 4, v228
	v_xor_b32_e32 v233, 8, v228
	v_writelane_b32 v254, s1, 15
	s_add_u32 s0, s14, 0xb400000
	s_addc_u32 s1, s15, 0
	v_writelane_b32 v254, s0, 16
	v_xor_b32_e32 v234, 16, v228
	v_xor_b32_e32 v235, 32, v228
	v_writelane_b32 v254, s1, 17
	s_add_u32 s0, s14, 0xb800000
	s_addc_u32 s1, s15, 0
	s_add_u32 s78, s14, 0x2c600000
	v_writelane_b32 v254, s0, 18
	s_addc_u32 s79, s15, 0
	v_mov_b32_e32 v236, 0xf0
	v_writelane_b32 v254, s1, 19
	s_add_u32 s0, s14, 0x8d00000
	v_writelane_b32 v254, s0, 20
	s_addc_u32 s0, s15, 0
	v_writelane_b32 v254, s0, 21
	s_add_u32 s0, s14, 0x2a200000
	v_writelane_b32 v254, s0, 22
	s_addc_u32 s0, s15, 0
	v_writelane_b32 v254, s0, 23
	s_add_u32 s0, s14, 0x8000
	v_writelane_b32 v254, s0, 24
	s_addc_u32 s0, s15, 0
	v_writelane_b32 v254, s0, 25
	s_add_u32 s0, s12, 0x4000000
	v_writelane_b32 v254, s0, 26
	s_addc_u32 s0, s13, 0
	v_writelane_b32 v254, s0, 27
	s_lshl_b32 s0, s62, 5
	s_and_b32 s0, s0, 0xe0
	s_ashr_i32 s1, s62, 3
	s_add_i32 s0, s0, s1
	s_cmpk_eq_i32 s60, 0x100
	s_cselect_b32 s4, s0, s62
	s_cmpk_lt_i32 s4, 0x300
	s_cselect_b64 s[0:1], -1, 0
	s_and_b32 s10, s4, 7
	s_cmpk_gt_i32 s4, 0x17f
	v_writelane_b32 v254, s0, 28
	s_cselect_b64 s[16:17], -1, 0
	v_cndmask_b32_e64 v1, 0, 1, s[16:17]
	v_writelane_b32 v254, s1, 29
	s_and_b64 s[0:1], s[16:17], exec
	s_cselect_b32 s0, 0xfffffe80, 0
	v_writelane_b32 v254, s4, 30
	s_add_i32 s0, s0, s4
	s_ashr_i32 s18, s0, 3
	v_writelane_b32 v254, s16, 31
	s_and_b64 s[0:1], s[16:17], exec
	s_cselect_b32 s4, s9, s7
	v_writelane_b32 v254, s17, 32
	v_writelane_b32 v254, s6, 33
	s_cselect_b32 s5, s8, s6
	s_ashr_i32 s19, s18, 31
	s_lshl_b64 s[0:1], s[18:19], 20
	v_writelane_b32 v254, s7, 34
	s_add_u32 s16, s5, s0
	s_mov_b32 s0, s18
	s_addc_u32 s17, s4, s1
	v_writelane_b32 v254, s0, 35
	s_lshl_b32 s4, s10, 20
	v_mov_b64_e32 v[200:201], 0x9c0
	v_writelane_b32 v254, s1, 36
	s_lshl_b32 s0, s18, 6
	v_writelane_b32 v254, s10, 37
	s_ashr_i32 s1, s0, 31
	v_writelane_b32 v254, s4, 38
	s_add_u32 s4, s16, 0x80000
	v_writelane_b32 v254, s16, 39
	s_addc_u32 s5, s17, 0
	v_mov_b64_e32 v[202:203], 0x9bf
	v_writelane_b32 v254, s17, 40
	v_writelane_b32 v254, s4, 41
	v_mov_b32_e32 v237, 0xcf
	s_movk_i32 s46, 0x1ff
	v_writelane_b32 v254, s5, 42
	s_add_u32 s4, s14, 0x16203800
	s_addc_u32 s5, s15, 0
	v_writelane_b32 v254, s4, 43
	s_and_b32 s81, s9, 0xffff
	s_cmp_lt_i32 s3, 0
	v_writelane_b32 v254, s5, 44
	s_movk_i32 s4, 0x139
	s_cselect_b32 s4, s4, 0x138
	s_mul_i32 s3, s3, s4
	s_add_i32 s3, s3, s2
	s_mul_hi_i32 s2, s3, 0x4ec4ec4f
	s_lshr_b32 s4, s2, 31
	s_ashr_i32 s2, s2, 6
	s_add_i32 s2, s2, s4
	s_mul_i32 s4, s2, 0xd0
	s_sub_i32 s3, s3, s4
	s_bfe_u32 s4, s3, 0x2001d
	s_add_i32 s4, s3, s4
	s_and_b32 s5, s4, 0xfffc
	s_sub_i32 s3, s3, s5
	s_lshl_b32 s2, s2, 2
	s_sext_i32_i16 s4, s4
	s_sext_i32_i16 s3, s3
	s_add_i32 s10, s2, s3
	s_ashr_i32 s2, s4, 2
	s_mul_i32 s100, s2, 35
	s_add_u32 s100, s100, 15
	s_mul_i32 s101, s100, 0x9d9
	s_lshr_b32 s101, s101, 17
	s_mul_i32 s101, s101, 52
	s_sub_u32 s2, s100, s101
	s_mov_b32 s100, s2
	v_writelane_b32 v254, s2, 45
	s_mov_b32 s2, s100
	s_bfe_i64 s[2:3], s[2:3], 0x100000
	s_lshl_b64 s[2:3], s[2:3], 20
	v_writelane_b32 v254, s2, 46
	s_ashr_i32 s11, s10, 31
	s_movk_i32 s18, 0x7fff
	v_writelane_b32 v254, s3, 47
	s_mov_b32 s2, s10
	v_writelane_b32 v254, s2, 48
	s_movk_i32 s52, 0x420
	s_movk_i32 s47, 0x2000
	v_writelane_b32 v254, s3, 49
	s_lshl_b64 s[2:3], s[10:11], 20
	s_add_u32 s4, s8, s2
	s_mul_i32 s2, s61, s60
	s_mul_i32 s2, s2, s33
	v_writelane_b32 v254, s2, 50
	s_addc_u32 s5, s9, s3
	v_writelane_b32 v254, s8, 51
	s_add_u32 s2, s4, 0x80000
	s_mov_b32 s80, s8
	v_writelane_b32 v254, s9, 52
	v_writelane_b32 v254, s4, 53
	s_addc_u32 s3, s5, 0
	s_lshl_b64 s[0:1], s[0:1], 2
	v_writelane_b32 v254, s5, 54
	v_writelane_b32 v254, s2, 55
	s_ashr_i32 s59, s58, 31
	s_add_i32 s56, 0, 0x23fc0
	v_writelane_b32 v254, s3, 56
	v_writelane_b32 v254, s0, 57
	s_movk_i32 s21, 0x90
	s_movk_i32 s53, 0xdff
	v_writelane_b32 v254, s1, 58
	v_readfirstlane_b32 s0, v1
	s_movk_i32 s20, 0x6800
	s_mov_b32 s33, 0x1000706
	v_writelane_b32 v254, s0, 59
	s_add_i32 s0, 0, 0x4000
	v_writelane_b32 v254, s0, 60
	s_add_i32 s0, 0, 0x23fd0
	v_writelane_b32 v254, s0, 61
	s_add_i32 s0, 0, 0x23fd4
	v_writelane_b32 v254, s0, 62
	s_add_i32 s0, 0, 0x12800
	v_writelane_b32 v254, s0, 63
	s_add_i32 s0, 0, 0x10100
	v_writelane_b32 v252, s0, 0
	s_add_i32 s0, 0, 0x1ad00
	v_writelane_b32 v252, s0, 1
	s_add_i32 s0, 0, 0x12500
	v_writelane_b32 v252, s0, 2
	s_add_i32 s0, 0, 0x16900
	v_writelane_b32 v252, s0, 3
	s_lshl_b64 s[0:1], s[58:59], 13
	v_writelane_b32 v252, s0, 4
	s_mov_b32 s97, 0
	s_mov_b32 s35, 0
	v_writelane_b32 v252, s1, 5
	s_mov_b64 s[0:1], -1
	v_writelane_b32 v252, s0, 6
	s_mov_b64 s[26:27], 0x1000
	s_mov_b64 s[30:31], 0x80
	v_writelane_b32 v252, s1, 7
	v_writelane_b32 v252, s62, 8
	v_writelane_b32 v252, s58, 9
	s_nop 1
	v_writelane_b32 v252, s59, 10
	v_writelane_b32 v252, s57, 11
	v_writelane_b32 v252, s56, 12
	v_writelane_b32 v252, s84, 13
	s_nop 1
	v_writelane_b32 v252, s85, 14
	s_branch .LBB0_200

.LBB0_309:
	s_add_i32 s49, s49, 1
	v_readlane_b32 s16, v254, 7
	s_mul_i32 s16, s49, s16
	s_mul_hi_u32 s17, s49, s60
	s_add_i32 s17, s17, s16
	s_mul_i32 s16, s49, s60
	s_add_u32 s16, s16, s62
	s_addc_u32 s17, s17, s57
	v_cmp_gt_i64_e32 vcc, s[16:17], v[202:203]
	v_cmp_lt_i64_e64 s[38:39], s[16:17], v[200:201]
	s_cbranch_vccnz .LBB0_311
	s_ashr_i32 s17, s16, 31
	s_lshr_b32 s17, s17, 29
	s_add_i32 s17, s16, s17
	s_ashr_i32 s28, s17, 3
	s_and_b32 s17, s17, -8
	s_sub_i32 s16, s16, s17
	s_cmp_lt_i32 s16, 0
	s_movk_i32 s17, 0x139
	s_cselect_b32 s17, s17, 0x138
	s_mul_i32 s16, s16, s17
	s_add_i32 s16, s16, s28
	s_mul_hi_i32 s17, s16, 0x4ec4ec4f
	s_lshr_b32 s28, s17, 31
	s_ashr_i32 s17, s17, 6
	s_add_i32 s17, s17, s28
	s_lshl_b32 s29, s17, 2
	s_sub_i32 s28, 48, s29
	s_min_i32 s36, s28, 4
	s_abs_i32 s28, s36
	v_cvt_f32_u32_e32 v2, s28
	s_sub_i32 s40, 0, s28
	s_mulk_i32 s17, 0xd0
	s_sub_i32 s16, s16, s17
	v_rcp_iflag_f32_e32 v2, v2
	s_abs_i32 s17, s16
	s_xor_b32 s37, s16, s36
	s_ashr_i32 s37, s37, 31
	v_mul_f32_e32 v2, 0x4f7ffffe, v2
	v_cvt_u32_f32_e32 v2, v2
	s_nop 0
	v_readfirstlane_b32 s41, v2
	s_mul_i32 s40, s40, s41
	s_mul_hi_u32 s40, s41, s40
	s_add_i32 s41, s41, s40
	s_mul_hi_u32 s40, s17, s41
	s_mul_i32 s41, s40, s28
	s_sub_i32 s17, s17, s41
	s_add_i32 s42, s40, 1
	s_sub_i32 s41, s17, s28
	s_cmp_ge_u32 s17, s28
	s_cselect_b32 s40, s42, s40
	s_cselect_b32 s17, s41, s17
	s_add_i32 s41, s40, 1
	s_cmp_ge_u32 s17, s28
	s_cselect_b32 s17, s41, s40
	s_xor_b32 s17, s17, s37
	s_sub_i32 s28, s17, s37
	s_mul_i32 s17, s28, s36
	s_sub_i32 s16, s16, s17
	s_add_i32 s36, s29, s16
	s_mul_i32 s16, s28, 35
	s_add_u32 s16, s16, 15
	s_mul_i32 s17, s16, 0x9d9
	s_lshr_b32 s17, s17, 17
	s_mul_i32 s17, s17, 52
	s_sub_u32 s28, s16, s17
